# norm phase: context-row split-K partial sums loaded 16 at a time with counted waits
# speedup vs baseline: 1.0702x; 1.0001x over previous
; __device__ __forceinline__ void norm_phase(const float* xs_lat, const float* xs_ctx, const float* partA, const float* partB, float* xc_wr, int row_begin, int rows, const float* gain, const float* modl, int shoff, int scoff, bf16_t* H, int gw, int NGW, int lane) {
;     ...
;             if (!lat && partA != nullptr) {
;                 const size_t ro = (size_t)(row - ML) * D;
; #pragma unroll
;                 for (int j = 0; j < 4; ++j) { const int ix = 64 * j + lane;
;                     v[u][j] = (((v[u][j] + ((const f32x4*)(partA + ro))[ix]) + ((const f32x4*)(partA + (size_t)MC * D + ro))[ix]) + ((const f32x4*)(partB + ro))[ix]) + ((const f32x4*)(partB + (size_t)MC * D + ro))[ix];
;                     ((f32x4*)(xc_wr + ro))[ix] = v[u][j]; }
;             }
;             float s = 0.f;
; #pragma unroll
;             for (int j = 0; j < 4; ++j) s += (v[u][j][0] * v[u][j][0] + v[u][j][1] * v[u][j][1]) + (v[u][j][2] * v[u][j][2] + v[u][j][3] * v[u][j][3]);
;             const float rstd = 1.0f / sqrtf(wave_sum(s) * (1.f / D) + EPS);
.LBB0_1162:
	s_or_b64 s[4:5], s[10:11], s[42:43]
	s_and_b64 vcc, exec, s[4:5]
	s_cbranch_vccnz .LBB0_1164
	s_lshl_b64 s[4:5], s[34:35], 12
	v_lshl_add_u64 v[72:73], v[42:43], 0, s[4:5]
	v_lshl_add_u64 v[74:75], v[44:45], 0, s[4:5]
	v_lshl_add_u64 v[54:55], v[46:47], 0, s[4:5]
	v_lshl_add_u64 v[56:57], v[48:49], 0, s[4:5]
	v_lshl_add_u64 v[52:53], v[50:51], 0, s[4:5]
	global_load_dwordx4 v[132:135], v[72:73], off
	global_load_dwordx4 v[160:163], v[74:75], off
	global_load_dwordx4 v[226:229], v[54:55], off
	global_load_dwordx4 v[176:179], v[56:57], off
	global_load_dwordx4 v[136:139], v[72:73], off offset:1024
	global_load_dwordx4 v[164:167], v[74:75], off offset:1024
	global_load_dwordx4 v[230:233], v[54:55], off offset:1024
	global_load_dwordx4 v[180:183], v[56:57], off offset:1024
	global_load_dwordx4 v[140:143], v[72:73], off offset:2048
	global_load_dwordx4 v[168:171], v[74:75], off offset:2048
	global_load_dwordx4 v[234:237], v[54:55], off offset:2048
	global_load_dwordx4 v[190:193], v[56:57], off offset:2048
	global_load_dwordx4 v[144:147], v[72:73], off offset:3072
	global_load_dwordx4 v[172:175], v[74:75], off offset:3072
	global_load_dwordx4 v[238:241], v[54:55], off offset:3072
	global_load_dwordx4 v[242:245], v[56:57], off offset:3072
	s_waitcnt vmcnt(12)
	v_pk_add_f32 v[22:23], v[22:23], v[134:135]
	v_pk_add_f32 v[20:21], v[20:21], v[132:133]
	v_pk_add_f32 v[22:23], v[22:23], v[162:163]
	v_pk_add_f32 v[20:21], v[20:21], v[160:161]
	v_pk_add_f32 v[22:23], v[22:23], v[228:229]
	v_pk_add_f32 v[20:21], v[20:21], v[226:227]
	v_pk_add_f32 v[22:23], v[22:23], v[178:179]
	v_pk_add_f32 v[20:21], v[20:21], v[176:177]
	global_store_dwordx4 v[52:53], v[20:23], off
	s_waitcnt vmcnt(9)
	v_pk_add_f32 v[30:31], v[30:31], v[138:139]
	v_pk_add_f32 v[28:29], v[28:29], v[136:137]
	v_pk_add_f32 v[30:31], v[30:31], v[166:167]
	v_pk_add_f32 v[28:29], v[28:29], v[164:165]
	v_pk_add_f32 v[30:31], v[30:31], v[232:233]
	v_pk_add_f32 v[28:29], v[28:29], v[230:231]
	v_pk_add_f32 v[30:31], v[30:31], v[182:183]
	v_pk_add_f32 v[28:29], v[28:29], v[180:181]
	global_store_dwordx4 v[52:53], v[28:31], off offset:1024
	s_waitcnt vmcnt(6)
	v_pk_add_f32 v[18:19], v[18:19], v[142:143]
	v_pk_add_f32 v[16:17], v[16:17], v[140:141]
	v_pk_add_f32 v[18:19], v[18:19], v[170:171]
	v_pk_add_f32 v[16:17], v[16:17], v[168:169]
	v_pk_add_f32 v[18:19], v[18:19], v[236:237]
	v_pk_add_f32 v[16:17], v[16:17], v[234:235]
	v_pk_add_f32 v[18:19], v[18:19], v[192:193]
	v_pk_add_f32 v[16:17], v[16:17], v[190:191]
	global_store_dwordx4 v[52:53], v[16:19], off offset:2048
	s_waitcnt vmcnt(3)
	v_pk_add_f32 v[26:27], v[26:27], v[146:147]
	v_pk_add_f32 v[24:25], v[24:25], v[144:145]
	v_pk_add_f32 v[26:27], v[26:27], v[174:175]
	v_pk_add_f32 v[24:25], v[24:25], v[172:173]
	v_pk_add_f32 v[26:27], v[26:27], v[240:241]
	v_pk_add_f32 v[24:25], v[24:25], v[238:239]
	v_pk_add_f32 v[26:27], v[26:27], v[244:245]
	v_pk_add_f32 v[24:25], v[24:25], v[242:243]
	global_store_dwordx4 v[52:53], v[24:27], off offset:3072
.LBB0_1164:
	s_waitcnt vmcnt(3)
	v_pk_mul_f32 v[52:53], v[22:23], v[22:23]
	v_pk_mul_f32 v[54:55], v[20:21], v[20:21]
	s_ashr_i32 s22, s3, 11
	v_pk_mov_b32 v[56:57], v[54:55], v[52:53] op_sel:[1,0]
	v_mov_b32_e32 v55, v53
	v_pk_add_f32 v[52:53], v[56:57], v[54:55]
	s_waitcnt vmcnt(2)
	v_pk_mul_f32 v[54:55], v[30:31], v[30:31]
	v_pk_add_f32 v[52:53], v[52:53], v[52:53] op_sel_hi:[0,1]
	v_pk_mul_f32 v[56:57], v[28:29], v[28:29]
	s_waitcnt vmcnt(1)
	v_mul_f32_e32 v52, v16, v16
	v_pk_mov_b32 v[68:69], v[56:57], v[54:55] op_sel:[1,0]
	v_mov_b32_e32 v57, v55
	v_pk_add_f32 v[54:55], v[68:69], v[56:57]
	v_pk_fma_f32 v[56:57], v[16:17], v[16:17], v[52:53] op_sel_hi:[1,1,0]
	v_mul_f32_e32 v52, v18, v18
	v_pk_add_f32 v[54:55], v[54:55], v[54:55] op_sel_hi:[0,1]
	v_pk_fma_f32 v[68:69], v[18:19], v[18:19], v[52:53] op_sel_hi:[1,1,0]
	s_waitcnt vmcnt(0)
	v_mul_f32_e32 v56, v24, v24
	v_mul_f32_e32 v68, v25, v25
	v_mul_f32_e32 v54, v26, v26
	v_mul_f32_e32 v52, v27, v27
	v_pk_add_f32 v[56:57], v[56:57], v[68:69]
	v_pk_add_f32 v[52:53], v[54:55], v[52:53]
	s_mul_i32 s23, s22, 0x1800
	v_pk_add_f32 v[52:53], v[56:57], v[52:53]
	s_mul_hi_i32 s22, s22, 0x1800
	v_add_f32_e32 v52, v52, v53
	ds_bpermute_b32 v53, v33, v52
	v_lshl_add_u64 v[76:77], s[16:17], 0, v[96:97]
	s_mov_b32 s25, 0x7000000
	s_waitcnt lgkmcnt(0)
	v_add_f32_e32 v52, v52, v53
	ds_bpermute_b32 v53, v58, v52
	s_waitcnt lgkmcnt(0)
	v_add_f32_e32 v52, v52, v53
	ds_bpermute_b32 v53, v59, v52
	s_waitcnt lgkmcnt(0)
	v_add_f32_e32 v52, v52, v53
	ds_bpermute_b32 v53, v60, v52
	s_waitcnt lgkmcnt(0)
	v_add_f32_e32 v52, v52, v53
	ds_bpermute_b32 v53, v61, v52
	s_waitcnt lgkmcnt(0)
	v_add_f32_e32 v52, v52, v53
	ds_bpermute_b32 v53, v62, v52
	s_waitcnt lgkmcnt(0)
; __device__ __forceinline__ unsigned cvt_pk_bf16(float lo, float hi) { unsigned r; asm volatile("v_cvt_pk_bf16_f32 %0, %1, %2" : "=v"(r) : "v"(lo), "v"(hi)); return r; }
; __device__ __forceinline__ void norm_phase(const float* xs_lat, const float* xs_ctx, const float* partA, const float* partB, float* xc_wr, int row_begin, int rows, const float* gain, const float* modl, int shoff, int scoff, bf16_t* H, int gw, int NGW, int lane) {
;     ...
;             const float rstd = 1.0f / sqrtf(wave_sum(s) * (1.f / D) + EPS);
;             const float* mb = modl + (size_t)b * NMOD;
;             u32x2* o8 = (u32x2*)(H + (size_t)row * D) + lane;
; #pragma unroll
;             for (int j = 0; j < 4; ++j) { const int c = 4 * (lane + 64 * j);
;                 const f32x4 g4 = *(const f32x4*)(gain + c), sc4 = *(const f32x4*)(mb + scoff + c), sh4 = *(const f32x4*)(mb + shoff + c);
;                 const f32x4 y = (v[u][j] * rstd * g4) * (sc4 + 1.0f) + sh4;
;                 u32x2 w; w.x = cvt_pk_bf16(y[0], y[1]); w.y = cvt_pk_bf16(y[2], y[3]); o8[64 * j] = w; }
	v_add_f32_e32 v52, v52, v53
	v_fmamk_f32 v52, v52, 0x3a800000, v221
	v_cmp_gt_f32_e32 vcc, s83, v52
	v_mul_f32_e32 v53, 0x4f800000, v52
	s_nop 0
	v_cndmask_b32_e32 v52, v52, v53, vcc
	v_sqrt_f32_e32 v53, v52
	s_nop 0
	v_add_u32_e32 v54, -1, v53
	v_fma_f32 v55, -v54, v53, v52
	v_cmp_ge_f32_e64 s[4:5], 0, v55
	v_add_u32_e32 v55, 1, v53
	s_nop 0
	v_cndmask_b32_e64 v54, v53, v54, s[4:5]
	v_fma_f32 v53, -v55, v53, v52
	v_cmp_lt_f32_e64 s[4:5], 0, v53
	s_nop 1
	v_cndmask_b32_e64 v53, v54, v55, s[4:5]
	v_mul_f32_e32 v54, 0x37800000, v53
	v_cndmask_b32_e32 v53, v53, v54, vcc
	v_cmp_class_f32_e32 vcc, v52, v222
	s_and_b64 s[4:5], s[42:43], exec
	s_nop 0
	v_cndmask_b32_e32 v52, v53, v52, vcc
	v_div_scale_f32 v53, s[4:5], v52, v52, 1.0
	v_rcp_f32_e32 v54, v53
	s_cselect_b32 s5, s22, 0
	s_cselect_b32 s4, s23, 0xc000
	s_lshl_b64 s[4:5], s[4:5], 2
	v_fma_f32 v55, -v53, v54, 1.0
	v_fmac_f32_e32 v54, v55, v54
	v_div_scale_f32 v55, vcc, 1.0, v52, 1.0
	s_add_u32 s22, s36, s4
	v_mul_f32_e32 v56, v55, v54
	s_addc_u32 s23, s37, s5
	v_fma_f32 v57, -v53, v56, v55
	s_add_u32 s4, s22, s0
	v_fmac_f32_e32 v56, v57, v54
	s_addc_u32 s5, s23, 0
	v_fma_f32 v53, -v53, v56, v55
	s_add_u32 s22, s22, s1
	v_div_fmas_f32 v53, v53, v54, v56
	s_addc_u32 s23, s23, 0
	global_load_dwordx4 v[54:57], v[34:35], off
	global_load_dwordx4 v[68:71], v63, s[4:5]
	global_load_dwordx4 v[72:75], v63, s[22:23]
	v_div_fixup_f32 v52, v53, v52, 1.0
	v_pk_mul_f32 v[22:23], v[22:23], v[52:53] op_sel_hi:[1,0]
	v_pk_mul_f32 v[20:21], v[20:21], v[52:53] op_sel_hi:[1,0]
	v_pk_mul_f32 v[30:31], v[30:31], v[52:53] op_sel_hi:[1,0]
	v_pk_mul_f32 v[28:29], v[28:29], v[52:53] op_sel_hi:[1,0]
	v_pk_mul_f32 v[18:19], v[18:19], v[52:53] op_sel_hi:[1,0]
	v_pk_mul_f32 v[16:17], v[16:17], v[52:53] op_sel_hi:[1,0]
	v_pk_mul_f32 v[24:25], v[24:25], v[52:53] op_sel_hi:[1,0]
	v_pk_mul_f32 v[26:27], v[26:27], v[52:53] op_sel_hi:[1,0]
	s_waitcnt vmcnt(2)
	v_pk_mul_f32 v[20:21], v[54:55], v[20:21]
	v_pk_mul_f32 v[22:23], v[56:57], v[22:23]
	s_waitcnt vmcnt(1)
	v_pk_add_f32 v[56:57], v[68:69], 1.0 op_sel_hi:[1,0]
	v_pk_add_f32 v[54:55], v[70:71], 1.0 op_sel_hi:[1,0]
	s_waitcnt vmcnt(0)
	v_pk_fma_f32 v[20:21], v[56:57], v[20:21], v[72:73]
	v_add_co_u32_e32 v72, vcc, s25, v76
	v_pk_fma_f32 v[22:23], v[54:55], v[22:23], v[74:75]
	s_nop 0
	v_addc_co_u32_e32 v73, vcc, 0, v77, vcc
	v_cvt_pk_bf16_f32 v20, v20, v21
	v_cvt_pk_bf16_f32 v21, v22, v23
	global_store_dwordx2 v[72:73], v[20:21], off
	global_load_dwordx4 v[20:23], v[36:37], off
	s_nop 0
	global_load_dwordx4 v[54:57], v64, s[4:5]
	global_load_dwordx4 v[68:71], v64, s[22:23]
	s_andn2_b64 vcc, exec, s[40:41]
	s_waitcnt vmcnt(2)
	v_pk_mul_f32 v[20:21], v[20:21], v[28:29]
	v_pk_mul_f32 v[22:23], v[22:23], v[30:31]
	s_waitcnt vmcnt(1)
	v_pk_add_f32 v[30:31], v[54:55], 1.0 op_sel_hi:[1,0]
	v_pk_add_f32 v[28:29], v[56:57], 1.0 op_sel_hi:[1,0]
	s_waitcnt vmcnt(0)
	v_pk_fma_f32 v[20:21], v[30:31], v[20:21], v[68:69]
	v_pk_fma_f32 v[22:23], v[28:29], v[22:23], v[70:71]
	v_cvt_pk_bf16_f32 v20, v20, v21
	s_nop 0
	v_cvt_pk_bf16_f32 v21, v22, v23
	global_store_dwordx2 v[72:73], v[20:21], off offset:512
	global_load_dwordx4 v[20:23], v[38:39], off
	s_nop 0
	global_load_dwordx4 v[28:31], v65, s[4:5]
	global_load_dwordx4 v[54:57], v65, s[22:23]
	s_waitcnt vmcnt(2)
	v_pk_mul_f32 v[16:17], v[20:21], v[16:17]
	v_pk_mul_f32 v[18:19], v[22:23], v[18:19]
	s_waitcnt vmcnt(1)
	v_pk_add_f32 v[22:23], v[28:29], 1.0 op_sel_hi:[1,0]
	v_pk_add_f32 v[20:21], v[30:31], 1.0 op_sel_hi:[1,0]
	s_waitcnt vmcnt(0)
	v_pk_fma_f32 v[16:17], v[22:23], v[16:17], v[54:55]
	v_pk_fma_f32 v[18:19], v[20:21], v[18:19], v[56:57]
	v_cvt_pk_bf16_f32 v16, v16, v17
	s_nop 0
	v_cvt_pk_bf16_f32 v17, v18, v19
	global_store_dwordx2 v[72:73], v[16:17], off offset:1024
	global_load_dwordx4 v[16:19], v[40:41], off
	s_nop 0
	global_load_dwordx4 v[20:23], v66, s[4:5]
	global_load_dwordx4 v[28:31], v66, s[22:23]
	s_waitcnt vmcnt(2)
	v_pk_mul_f32 v[16:17], v[24:25], v[16:17]
	s_waitcnt vmcnt(1)
	v_pk_add_f32 v[20:21], v[20:21], 1.0 op_sel_hi:[1,0]
	v_pk_mul_f32 v[18:19], v[26:27], v[18:19]
	v_pk_add_f32 v[22:23], v[22:23], 1.0 op_sel_hi:[1,0]
	s_waitcnt vmcnt(0)
	v_pk_fma_f32 v[16:17], v[16:17], v[20:21], v[28:29]
	v_pk_fma_f32 v[18:19], v[18:19], v[22:23], v[30:31]
	v_cvt_pk_bf16_f32 v16, v16, v17
	s_nop 0
	v_cvt_pk_bf16_f32 v17, v18, v19
	global_store_dwordx2 v[72:73], v[16:17], off offset:1536
	s_cbranch_vccnz .LBB0_1159
; __device__ __forceinline__ void norm_phase(const float* xs_lat, const float* xs_ctx, const float* partA, const float* partB, float* xc_wr, int row_begin, int rows, const float* gain, const float* modl, int shoff, int scoff, bf16_t* H, int gw, int NGW, int lane) {
;     ...
;             if (!lat && partA != nullptr) {
;                 const size_t ro = (size_t)(row - ML) * D;
; #pragma unroll
;                 for (int j = 0; j < 4; ++j) { const int ix = 64 * j + lane;
;                     v[u][j] = (((v[u][j] + ((const f32x4*)(partA + ro))[ix]) + ((const f32x4*)(partA + (size_t)MC * D + ro))[ix]) + ((const f32x4*)(partB + ro))[ix]) + ((const f32x4*)(partB + (size_t)MC * D + ro))[ix];
;                     ((f32x4*)(xc_wr + ro))[ix] = v[u][j]; }
;             }
	s_or_b64 s[4:5], s[10:11], s[30:31]
	s_and_b64 vcc, exec, s[4:5]
	s_cbranch_vccnz .LBB0_1158
	s_add_i32 s34, s24, 0xffffc000
	s_lshl_b64 s[4:5], s[34:35], 12
	v_lshl_add_u64 v[26:27], v[42:43], 0, s[4:5]
	v_lshl_add_u64 v[28:29], v[44:45], 0, s[4:5]
	v_lshl_add_u64 v[18:19], v[46:47], 0, s[4:5]
	v_lshl_add_u64 v[20:21], v[48:49], 0, s[4:5]
	v_lshl_add_u64 v[16:17], v[50:51], 0, s[4:5]
	global_load_dwordx4 v[132:135], v[26:27], off
	global_load_dwordx4 v[160:163], v[28:29], off
	global_load_dwordx4 v[226:229], v[18:19], off
	global_load_dwordx4 v[176:179], v[20:21], off
	global_load_dwordx4 v[136:139], v[26:27], off offset:1024
	global_load_dwordx4 v[164:167], v[28:29], off offset:1024
	global_load_dwordx4 v[230:233], v[18:19], off offset:1024
	global_load_dwordx4 v[180:183], v[20:21], off offset:1024
	global_load_dwordx4 v[140:143], v[26:27], off offset:2048
	global_load_dwordx4 v[168:171], v[28:29], off offset:2048
	global_load_dwordx4 v[234:237], v[18:19], off offset:2048
	global_load_dwordx4 v[190:193], v[20:21], off offset:2048
	global_load_dwordx4 v[144:147], v[26:27], off offset:3072
	global_load_dwordx4 v[172:175], v[28:29], off offset:3072
	global_load_dwordx4 v[238:241], v[18:19], off offset:3072
	global_load_dwordx4 v[242:245], v[20:21], off offset:3072
	s_waitcnt vmcnt(12)
	v_pk_add_f32 v[6:7], v[6:7], v[134:135]
	v_pk_add_f32 v[4:5], v[4:5], v[132:133]
	v_pk_add_f32 v[6:7], v[6:7], v[162:163]
	v_pk_add_f32 v[4:5], v[4:5], v[160:161]
	v_pk_add_f32 v[6:7], v[6:7], v[228:229]
	v_pk_add_f32 v[4:5], v[4:5], v[226:227]
	v_pk_add_f32 v[6:7], v[6:7], v[178:179]
	v_pk_add_f32 v[4:5], v[4:5], v[176:177]
	global_store_dwordx4 v[16:17], v[4:7], off
	s_waitcnt vmcnt(9)
	v_pk_add_f32 v[10:11], v[10:11], v[138:139]
	v_pk_add_f32 v[8:9], v[8:9], v[136:137]
	v_pk_add_f32 v[10:11], v[10:11], v[166:167]
	v_pk_add_f32 v[8:9], v[8:9], v[164:165]
	v_pk_add_f32 v[10:11], v[10:11], v[232:233]
	v_pk_add_f32 v[8:9], v[8:9], v[230:231]
	v_pk_add_f32 v[10:11], v[10:11], v[182:183]
	v_pk_add_f32 v[8:9], v[8:9], v[180:181]
	global_store_dwordx4 v[16:17], v[8:11], off offset:1024
	s_waitcnt vmcnt(6)
	v_pk_add_f32 v[2:3], v[2:3], v[142:143]
	v_pk_add_f32 v[0:1], v[0:1], v[140:141]
	v_pk_add_f32 v[2:3], v[2:3], v[170:171]
	v_pk_add_f32 v[0:1], v[0:1], v[168:169]
	v_pk_add_f32 v[2:3], v[2:3], v[236:237]
	v_pk_add_f32 v[0:1], v[0:1], v[234:235]
	v_pk_add_f32 v[2:3], v[2:3], v[192:193]
	v_pk_add_f32 v[0:1], v[0:1], v[190:191]
	global_store_dwordx4 v[16:17], v[0:3], off offset:2048
	s_waitcnt vmcnt(3)
	v_pk_add_f32 v[14:15], v[14:15], v[146:147]
	v_pk_add_f32 v[12:13], v[12:13], v[144:145]
	v_pk_add_f32 v[14:15], v[14:15], v[174:175]
	v_pk_add_f32 v[12:13], v[12:13], v[172:173]
	v_pk_add_f32 v[14:15], v[14:15], v[240:241]
	v_pk_add_f32 v[12:13], v[12:13], v[238:239]
	v_pk_add_f32 v[14:15], v[14:15], v[244:245]
	v_pk_add_f32 v[12:13], v[12:13], v[242:243]
	global_store_dwordx4 v[16:17], v[12:15], off offset:3072
	s_branch .LBB0_1158
